# barrier-nonleaders-poll-topgen
# speedup vs baseline: 1.0637x; 1.0071x over previous
.LBB0_993:
	v_readlane_b32 s6, v251, 53
	v_readlane_b32 s7, v251, 54
	s_add_u32 s6, s4, s6
	s_addc_u32 s7, s5, s7
	v_mov_b64_e32 v[4:5], s[6:7]
	flat_atomic_add v4, v[4:5], v217 sc0
	v_cvt_f32_u32_e32 v3, v2
	v_sub_u32_e32 v5, 0, v2
	v_rcp_iflag_f32_e32 v3, v3
	s_nop 0
	v_mul_f32_e32 v3, 0x4f7ffffe, v3
	v_cvt_u32_f32_e32 v3, v3
	v_mul_lo_u32 v5, v5, v3
	v_mul_hi_u32 v5, v3, v5
	v_add_u32_e32 v3, v3, v5
	s_waitcnt vmcnt(0) lgkmcnt(0)
	v_mul_hi_u32 v3, v4, v3
	v_mul_lo_u32 v5, v3, v2
	v_sub_u32_e32 v5, v4, v5
	v_cmp_ge_u32_e32 vcc, v5, v2
	v_add_u32_e32 v6, 1, v3
	s_nop 0
	v_cndmask_b32_e32 v3, v3, v6, vcc
	v_sub_u32_e32 v6, v5, v2
	v_cndmask_b32_e32 v5, v5, v6, vcc
	v_cmp_ge_u32_e32 vcc, v5, v2
	v_add_u32_e32 v5, 1, v3
	v_add_u32_e32 v6, 1, v4
	v_cndmask_b32_e32 v3, v3, v5, vcc
	v_mad_u64_u32 v[4:5], s[6:7], v2, v3, v[2:3]
	v_cmp_ne_u32_e32 vcc, v6, v4
	s_and_saveexec_b64 s[6:7], vcc
	s_xor_b64 s[6:7], exec, s[6:7]
	s_cbranch_execz .LBB0_1006
	v_readlane_b32 s8, v251, 29
	v_readlane_b32 s9, v251, 30
	s_lshl_b64 s[8:9], s[8:9], 2
	s_add_u32 s10, s4, 0x3500
	s_addc_u32 s11, s5, 0
	v_mov_b64_e32 v[4:5], s[10:11]
	flat_load_dword v0, v[4:5] sc1
	s_waitcnt vmcnt(0) lgkmcnt(0)
	v_cmp_eq_u32_e32 vcc, v0, v3
	s_and_saveexec_b64 s[8:9], vcc
	s_cbranch_execz .LBB0_1005
	s_mov_b32 s34, 1
	s_mov_b64 s[12:13], 0
	s_branch .LBB0_997
